# deferred transposes guarded by gridDim==256 (phase 0 does all tiles otherwise); otherwise same as previous
# speedup vs baseline: 1.0090x; 1.0033x over previous
.LBB0_17:
	s_load_dwordx16 s[4:19], s[0:1], 0x40
	s_cmp_lt_i32 s24, 1
	s_waitcnt lgkmcnt(0)
	v_writelane_b32 v230, s4, 0
	s_nop 1
	v_writelane_b32 v230, s5, 1
	v_writelane_b32 v230, s6, 2
	v_writelane_b32 v230, s7, 3
	v_writelane_b32 v230, s8, 4
	v_writelane_b32 v230, s9, 5
	v_writelane_b32 v230, s10, 6
	v_writelane_b32 v230, s11, 7
	v_writelane_b32 v230, s12, 8
	v_writelane_b32 v230, s13, 9
	v_writelane_b32 v230, s14, 10
	v_writelane_b32 v230, s15, 11
	v_writelane_b32 v230, s16, 12
	v_writelane_b32 v230, s17, 13
	v_writelane_b32 v230, s18, 14
	v_writelane_b32 v230, s19, 15
	s_cselect_b64 s[4:5], -1, 0
	s_cmp_gt_i32 s25, 0
	s_cselect_b64 s[6:7], -1, 0
	s_and_b64 s[4:5], s[4:5], s[6:7]
	s_andn2_b64 vcc, exec, s[4:5]
	s_cbranch_vccnz .LBB0_147
	s_lshl_b32 s3, s2, 1
	s_cmpk_gt_i32 s3, 0x173f
	s_cbranch_scc1 .LBB0_75
	v_lshlrev_b32_e32 v0, 3, v129
	s_load_dword s4, s[0:1], 0x148
	v_lshrrev_b32_e32 v14, 8, v129
	v_and_b32_e32 v0, 56, v0
	v_bfe_u32 v18, v129, 3, 5
	v_lshl_add_u32 v2, v14, 15, 0
	v_and_b32_e32 v15, 63, v129
	v_and_b32_e32 v3, 16, v129
	v_mul_u32_u24_e32 v5, 0x104, v0
	v_lshlrev_b32_e32 v6, 2, v18
	v_bfe_u32 v16, v129, 6, 2
	v_lshl_add_u32 v4, v15, 2, v2
	v_add3_u32 v19, v2, v5, v6
	v_mov_b32_e32 v2, s57
	v_mov_b32_e32 v6, s55
	v_cmp_eq_u32_e32 vcc, 0, v3
	v_mul_u32_u24_e32 v5, 0x104, v16
	v_and_b32_e32 v17, 15, v129
	v_cndmask_b32_e32 v3, v2, v6, vcc
	v_mov_b32_e32 v2, s56
	v_mov_b32_e32 v6, s54
	v_mov_b32_e32 v1, 0
	s_waitcnt lgkmcnt(0)
	s_lshl_b32 s16, s4, 1
	s_movk_i32 s17, 0x1740
	s_cmpk_lg_i32 s4, 0x100
	s_cbranch_scc1 .Ltr_full
	s_movk_i32 s17, 0x340
.Ltr_full:
	v_or_b32_e32 v20, 32, v18
	v_cndmask_b32_e32 v2, v2, v6, vcc
	v_add_u32_e32 v21, v4, v5
	v_lshlrev_b32_e32 v0, 1, v0
	s_branch .LBB0_21
.LBB0_20:
	s_or_b64 exec, exec, s[4:5]
	s_waitcnt vmcnt(0)
	ds_write_b32 v21, v12
	ds_write_b32 v21, v11 offset:1040
	ds_write_b32 v21, v26 offset:2080
	ds_write_b32 v21, v25 offset:3120
	ds_write_b32 v21, v28 offset:4160
	ds_write_b32 v21, v27 offset:5200
	ds_write_b32 v21, v30 offset:6240
	ds_write_b32 v21, v29 offset:7280
	ds_write_b32 v21, v32 offset:8320
	ds_write_b32 v21, v31 offset:9360
	ds_write_b32 v21, v34 offset:10400
	ds_write_b32 v21, v33 offset:11440
	ds_write_b32 v21, v36 offset:12480
	ds_write_b32 v21, v35 offset:13520
	ds_write_b32 v21, v38 offset:14560
	ds_write_b32 v21, v37 offset:15600
	v_ashrrev_i32_e32 v11, 31, v10
	s_waitcnt lgkmcnt(0)
	s_barrier
	v_lshl_add_u64 v[4:5], v[10:11], 1, v[4:5]
	ds_read2_b32 v[8:9], v19 offset1:32
	ds_read2_b32 v[10:11], v19 offset0:65 offset1:97
	ds_read2_b32 v[12:13], v19 offset0:130 offset1:162
	ds_read2_b32 v[24:25], v19 offset0:195 offset1:227
	v_add_u32_e32 v6, 0x400, v19
	ds_read2_b32 v[26:27], v6 offset0:4 offset1:36
	ds_read2_b32 v[28:29], v6 offset0:69 offset1:101
	ds_read2_b32 v[30:31], v6 offset0:134 offset1:166
	ds_read2_b32 v[32:33], v6 offset0:199 offset1:231
	v_lshl_add_u64 v[34:35], v[4:5], 0, v[0:1]
	s_waitcnt lgkmcnt(6)
	v_cvt_pk_bf16_f32 v4, v8, v10
	v_or_b32_e32 v8, v23, v18
	v_ashrrev_i32_e32 v10, 31, v23
	v_mul_lo_u32 v10, v10, v22
	v_mad_u64_u32 v[36:37], s[4:5], v8, v22, 0
	v_add_u32_e32 v37, v37, v10
	s_waitcnt lgkmcnt(4)
	v_cvt_pk_bf16_f32 v5, v12, v24
	s_waitcnt lgkmcnt(2)
	v_cvt_pk_bf16_f32 v6, v26, v28
	s_waitcnt lgkmcnt(0)
	v_cvt_pk_bf16_f32 v7, v30, v32
	v_lshl_add_u64 v[36:37], v[36:37], 1, v[34:35]
	v_or_b32_e32 v8, v23, v20
	global_store_dwordx4 v[36:37], v[4:7], off
	s_add_i32 s3, s3, s16
	s_cmp_lt_i32 s3, s17
	v_cvt_pk_bf16_f32 v4, v9, v11
	v_mad_u64_u32 v[8:9], s[4:5], v8, v22, 0
	v_add_u32_e32 v9, v9, v10
	v_cvt_pk_bf16_f32 v5, v13, v25
	v_cvt_pk_bf16_f32 v6, v27, v29
	v_cvt_pk_bf16_f32 v7, v31, v33
	v_lshl_add_u64 v[8:9], v[8:9], 1, v[34:35]
	global_store_dwordx4 v[8:9], v[4:7], off
	s_cbranch_scc0 .LBB0_75

.LBB0_362:
	s_cmp_lt_u32 s2, 128
	s_cbranch_scc1 .Ltrq_skip
	s_load_dword s4, s[0:1], 0x148
	s_waitcnt lgkmcnt(0)
	s_cmpk_lg_i32 s4, 0x100
	s_cbranch_scc1 .Ltrq_skip
	s_sub_u32 s3, s2, 128
	s_lshl_b32 s3, s3, 1
	s_addk_i32 s3, 0x340
	s_cmpk_gt_i32 s3, 0x173f
	s_cbranch_scc1 .Ltrq_done
	s_load_dwordx4 s[72:75], s[0:1], 0x48
	s_load_dwordx2 s[76:77], s[0:1], 0x78
	s_load_dwordx2 s[78:79], s[0:1], 0x80
	s_load_dwordx4 s[80:83], s[0:1], 0xc8
	s_load_dwordx4 s[84:87], s[0:1], 0x100
	v_and_b32_e32 v32, 63, v129
	v_lshlrev_b32_e32 v82, 2, v32
	v_mov_b32_e32 v83, 0
	v_lshrrev_b32_e32 v84, 5, v32
	v_lshlrev_b32_e32 v84, 4, v84
	v_and_b32_e32 v85, 15, v32
	v_add_u32_e32 v84, v84, v85
	v_lshlrev_b32_e32 v84, 2, v84
	v_mov_b32_e32 v85, 0
	v_and_b32_e32 v37, 16, v32
	v_cmp_ne_u32_e64 s[68:69], 0, v37
	v_readfirstlane_b32 s4, v129
	s_lshr_b32 s4, s4, 6
	s_lshr_b32 s5, s4, 2
	s_and_b32 s6, s4, 3
	s_lshl_b32 s7, s5, 15
	s_mul_i32 s8, s6, 0x104
	s_add_u32 s8, s7, s8
	v_add_u32_e32 v38, s8, v82
	v_and_b32_e32 v39, 7, v129
	v_lshlrev_b32_e32 v39, 3, v39
	v_mul_u32_u24_e32 v40, 0x104, v39
	v_bfe_u32 v41, v129, 3, 5
	v_lshl_add_u32 v40, v41, 2, v40
	v_add_u32_e32 v40, s7, v40
	v_add_u32_e32 v44, 0x400, v40
	v_lshlrev_b32_e32 v42, 1, v39
	v_mov_b32_e32 v47, 0
	s_add_u32 s9, s3, s5
	s_waitcnt lgkmcnt(0)
	s_cmpk_lt_u32 s9, 0x440
	s_cbranch_scc1 .Ltrq_p1_c0
	s_cmpk_lt_u32 s9, 0xc40
	s_cbranch_scc1 .Ltrq_p1_c1
	s_cmpk_lt_u32 s9, 0x1440
	s_cbranch_scc1 .Ltrq_p1_c2
	s_cmpk_lt_u32 s9, 0x1540
	s_cbranch_scc1 .Ltrq_p1_c3
	s_sub_u32 s7, s9, 0x1540
	s_mov_b64 s[70:71], s[80:81]
	s_mov_b64 s[12:13], s[82:83]
	s_mov_b64 s[16:17], s[86:87]
	s_mov_b32 s8, 10
	s_mov_b32 s22, 10
	s_mov_b32 s21, 1
	s_branch .Ltrq_p1_cm
